# MLA attention: softmax row-sum adds moved from the pre-PV block into the PV MFMA gaps (single f32 chain)
# speedup vs baseline: 1.0487x; 1.0038x over previous
; #define PIN() do { asm volatile("" ::: "memory"); __builtin_amdgcn_sched_barrier(0); } while (0)
; #define MFMA(a, b, c) __builtin_amdgcn_mfma_f32_32x32x16_bf16((a), (b), (c), 0, 0, 0)
; DI unsigned pk2(float a, float b) { f32x2_t v = {a, b}; bf16x2_t r = __builtin_convertvector(v, bf16x2_t); return __builtin_bit_cast(unsigned, r); }
; #define VLD(dst_, s4_) do { _Pragma("unroll") for (int db = 0; db < 4; ++db) dst_[db].v = *(const bf16x8*)(vbase + db * 32 * VSTR + (s4_) * 32); } while (0)
; template <int DQK, int NM>
; DI void attn_item(const bf16_t* Qb, const bf16_t* Kb, size_t mstride, const bf16_t* VTb,
;                   int q0, int nkt, float cs, bf16_t* Orow  , float lam, float outscale, const float* subw, char* smem) {
;     ...
;     {
;       const f32x2_t cs2 = {cs, cs}, mc2 = {mrun * cs, mrun * cs};
;       f32x2_t ps2 = {0.f, 0.f};
; #pragma unroll
;       for (int kb = 0; kb < 2; ++kb)
; #pragma unroll
;         for (int i = 0; i < 16; i += 2) {
;           f32x2_t t = {sacc[kb][i], sacc[kb][i + 1]};
;           t = t * cs2 - mc2;
;           t.x = __builtin_amdgcn_exp2f(t.x); t.y = __builtin_amdgcn_exp2f(t.y);
;           sacc[kb][i] = t.x; sacc[kb][i + 1] = t.y;
;           ps2 = ps2 + t;
;         }
;       lrun += ps2.x + ps2.y;
;     }
;     const char* vbase = cur + KT_BYTES + l31 * VSTR + hh * 16;
;     {
;       struct VF { bf16x8 v; };
;       VF vfa[4], vfb[4];
;     ...
;       VLD(vfa, 0);
; #pragma unroll
;       for (int s4 = 0; s4 < 4; ++s4) {
;         const int kb = s4 >> 1, sp = s4 & 1;
;         PIN();
;         if (s4 < 3) { if (s4 & 1) VLD(vfa, s4 + 1); else VLD(vfb, s4 + 1); }
;         union { bf16x8 v; unsigned u[4]; } pf;
; #pragma unroll
;         for (int e = 0; e < 4; ++e) pf.u[e] = pk2(sacc[kb][8 * sp + 2 * e], sacc[kb][8 * sp + 2 * e + 1]);
;         PIN();
; #pragma unroll
;         for (int db = 0; db < 4; ++db) { if (s4 & 1) oacc[db] = MFMA(vfb[db].v, pf.v, oacc[db]); else oacc[db] = MFMA(vfa[db].v, pf.v, oacc[db]); }
;         {
;           char* b_ = smem + ((kt + 1) & 1) * BUF;
;           if (s4 == 0) { *(uint4*)(b_ + klo[0]) = kreg0; if (NKC > 2) *(uint4*)(b_ + klo[2]) = kreg2; }
;           if (s4 == 1) { *(uint4*)(b_ + klo[1]) = kreg1; }
;           if (s4 == 2) { *(uint4*)(b_ + vlo0) = vreg0; }
;           if (s4 == 3) { *(uint4*)(b_ + vlo1) = vreg1; }
;         }
;       }
.LBB0_126:
	v_mul_f32_e32 v196, 0x3dd53b95, v218
	v_fma_f32 v80, v80, s26, -v196
	v_fma_f32 v81, v81, s26, -v196
	v_fma_f32 v64, v64, s26, -v196
	v_fma_f32 v65, v65, s26, -v196
	v_exp_f32_e32 v220, v80
	v_exp_f32_e32 v221, v81
	v_fma_f32 v80, v82, s26, -v196
	v_fma_f32 v81, v83, s26, -v196
	v_fma_f32 v82, v88, s26, -v196
	v_fma_f32 v83, v89, s26, -v196
	v_exp_f32_e32 v222, v80
	v_exp_f32_e32 v223, v81
	v_fma_f32 v80, v84, s26, -v196
	v_fma_f32 v81, v85, s26, -v196
	v_exp_f32_e32 v228, v82
	v_exp_f32_e32 v224, v80
	v_exp_f32_e32 v225, v81
	v_fma_f32 v80, v86, s26, -v196
	v_fma_f32 v81, v87, s26, -v196
	v_exp_f32_e32 v229, v83
	v_exp_f32_e32 v226, v80
	v_exp_f32_e32 v227, v81
	v_fma_f32 v82, v90, s26, -v196
	v_fma_f32 v83, v91, s26, -v196
	v_exp_f32_e32 v230, v82
	v_exp_f32_e32 v231, v83
	v_fma_f32 v82, v92, s26, -v196
	v_fma_f32 v83, v93, s26, -v196
	v_exp_f32_e32 v232, v82
	v_exp_f32_e32 v233, v83
	v_fma_f32 v82, v94, s26, -v196
	v_fma_f32 v83, v95, s26, -v196
	v_exp_f32_e32 v234, v82
	v_exp_f32_e32 v235, v83
	v_exp_f32_e32 v236, v64
	v_exp_f32_e32 v237, v65
	v_fma_f32 v64, v66, s26, -v196
	v_fma_f32 v65, v67, s26, -v196
	v_exp_f32_e32 v238, v64
	v_exp_f32_e32 v239, v65
	v_fma_f32 v64, v68, s26, -v196
	v_fma_f32 v65, v69, s26, -v196
	v_exp_f32_e32 v240, v64
	v_exp_f32_e32 v241, v65
	v_fma_f32 v64, v70, s26, -v196
	v_fma_f32 v65, v71, s26, -v196
	v_exp_f32_e32 v242, v64
	v_exp_f32_e32 v243, v65
	v_fma_f32 v66, v72, s26, -v196
	v_fma_f32 v67, v73, s26, -v196
	v_exp_f32_e32 v244, v66
	v_exp_f32_e32 v245, v67
	v_fma_f32 v66, v74, s26, -v196
	v_fma_f32 v67, v75, s26, -v196
	v_exp_f32_e32 v246, v66
	v_exp_f32_e32 v247, v67
	v_fma_f32 v66, v76, s26, -v196
	v_fma_f32 v67, v77, s26, -v196
	v_exp_f32_e32 v248, v66
	v_exp_f32_e32 v249, v67
	v_fma_f32 v66, v78, s26, -v196
	v_fma_f32 v67, v79, s26, -v196
	v_exp_f32_e32 v250, v66
	v_exp_f32_e32 v251, v67
	v_add3_u32 v219, s25, v214, v170
	s_cmp_eq_u32 s24, 1
	s_cselect_b32 s24, 0xac00, 0
	ds_read_b128 v[64:67], v219 offset:25600
	ds_read_b128 v[68:71], v219 offset:30208
	ds_read_b128 v[72:75], v219 offset:34816
	ds_read_b128 v[76:79], v219 offset:39424
	s_add_i32 s24, s24, 0
	v_add_u32_e32 v206, s24, v197
	v_add_u32_e32 v211, s24, v216
	ds_read_b128 v[80:83], v219 offset:25632
	ds_read_b128 v[84:87], v219 offset:30240
	ds_read_b128 v[88:91], v219 offset:34848
	ds_read_b128 v[92:95], v219 offset:39456
	v_add_f32_e32 v203, v220, v221
	v_add_f32_e32 v203, v222, v203
	v_add_f32_e32 v203, v223, v203
	v_add_f32_e32 v203, v224, v203
	v_add_f32_e32 v203, v225, v203
	v_add_f32_e32 v203, v226, v203
	v_add_f32_e32 v203, v227, v203
	v_cvt_pk_bf16_f32 v220, v220, v221
	v_cvt_pk_bf16_f32 v221, v222, v223
	v_cvt_pk_bf16_f32 v222, v224, v225
	v_cvt_pk_bf16_f32 v223, v226, v227
	s_waitcnt lgkmcnt(7)
	s_nop 0
	v_mfma_f32_32x32x16_bf16 v[32:47], v[64:67], v[220:223], v[32:47]
	v_add_f32_e32 v203, v228, v203
	v_add_f32_e32 v203, v229, v203
	s_waitcnt vmcnt(4)
	ds_write_b128 v206, v[158:161]
	s_waitcnt vmcnt(2)
	ds_write_b128 v211, v[162:165]
	s_waitcnt lgkmcnt(8)
	v_mfma_f32_32x32x16_bf16 v[48:63], v[68:71], v[220:223], v[48:63]
	v_add_f32_e32 v203, v230, v203
	v_add_f32_e32 v203, v231, v203
	s_waitcnt lgkmcnt(7)
	v_mfma_f32_32x32x16_bf16 v[16:31], v[72:75], v[220:223], v[16:31]
	v_add_f32_e32 v203, v232, v203
	v_add_f32_e32 v203, v233, v203
	s_waitcnt lgkmcnt(6)
	v_mfma_f32_32x32x16_bf16 v[0:15], v[76:79], v[220:223], v[0:15]
	v_add_f32_e32 v203, v234, v203
	v_add_f32_e32 v203, v235, v203
	ds_read_b128 v[64:67], v219 offset:25664
	ds_read_b128 v[68:71], v219 offset:30272
	ds_read_b128 v[72:75], v219 offset:34880
	ds_read_b128 v[76:79], v219 offset:39488
	v_cvt_pk_bf16_f32 v158, v228, v229
	v_cvt_pk_bf16_f32 v159, v230, v231
	v_cvt_pk_bf16_f32 v160, v232, v233
	v_cvt_pk_bf16_f32 v161, v234, v235
	s_waitcnt lgkmcnt(9)
	s_nop 0
	v_mfma_f32_32x32x16_bf16 v[32:47], v[80:83], v[158:161], v[32:47]
	v_add_f32_e32 v203, v236, v203
	v_add_f32_e32 v203, v237, v203
	v_add_u32_e32 v80, s24, v215
	ds_write_b128 v80, v[154:157]
	s_waitcnt lgkmcnt(9)
	v_mfma_f32_32x32x16_bf16 v[48:63], v[84:87], v[158:161], v[48:63]
	v_add_f32_e32 v203, v238, v203
	v_add_f32_e32 v203, v239, v203
	s_waitcnt lgkmcnt(8)
	v_mfma_f32_32x32x16_bf16 v[16:31], v[88:91], v[158:161], v[16:31]
	v_add_f32_e32 v203, v240, v203
	v_add_f32_e32 v203, v241, v203
	s_waitcnt lgkmcnt(7)
	v_mfma_f32_32x32x16_bf16 v[0:15], v[92:95], v[158:161], v[0:15]
	v_add_f32_e32 v203, v242, v203
	v_add_f32_e32 v203, v243, v203
	ds_read_b128 v[80:83], v219 offset:25696
	ds_read_b128 v[84:87], v219 offset:30304
	ds_read_b128 v[88:91], v219 offset:34912
	ds_read_b128 v[92:95], v219 offset:39520
	v_cvt_pk_bf16_f32 v154, v236, v237
	v_cvt_pk_bf16_f32 v155, v238, v239
	v_cvt_pk_bf16_f32 v156, v240, v241
	v_cvt_pk_bf16_f32 v157, v242, v243
	s_waitcnt lgkmcnt(8)
	s_nop 0
	v_mfma_f32_32x32x16_bf16 v[32:47], v[64:67], v[154:157], v[32:47]
	v_add_f32_e32 v203, v244, v203
	v_add_f32_e32 v203, v245, v203
	v_add_u32_e32 v64, s24, v182
	s_waitcnt vmcnt(1)
	ds_write_b128 v64, v[150:153] offset:25600
	s_waitcnt lgkmcnt(8)
	v_mfma_f32_32x32x16_bf16 v[48:63], v[68:71], v[154:157], v[48:63]
	v_add_f32_e32 v203, v246, v203
	v_add_f32_e32 v203, v247, v203
	s_waitcnt lgkmcnt(7)
	v_mfma_f32_32x32x16_bf16 v[16:31], v[72:75], v[154:157], v[16:31]
	v_add_f32_e32 v203, v248, v203
	v_add_f32_e32 v203, v249, v203
	s_waitcnt lgkmcnt(6)
	v_mfma_f32_32x32x16_bf16 v[0:15], v[76:79], v[154:157], v[0:15]
	v_add_f32_e32 v203, v250, v203
	v_add_f32_e32 v203, v251, v203
	v_cvt_pk_bf16_f32 v64, v244, v245
	v_cvt_pk_bf16_f32 v65, v246, v247
	v_cvt_pk_bf16_f32 v66, v248, v249
	v_cvt_pk_bf16_f32 v67, v250, v251
	s_waitcnt lgkmcnt(4)
	s_nop 0
	v_mfma_f32_32x32x16_bf16 v[32:47], v[80:83], v[64:67], v[32:47]
	v_add_u32_e32 v68, s24, v184
	s_waitcnt vmcnt(0)
	ds_write_b128 v68, v[146:149] offset:25600
	v_add_f32_e32 v185, v185, v203
	s_waitcnt lgkmcnt(4)
	v_mfma_f32_32x32x16_bf16 v[48:63], v[84:87], v[64:67], v[48:63]
	s_waitcnt lgkmcnt(3)
	v_mfma_f32_32x32x16_bf16 v[16:31], v[88:91], v[64:67], v[16:31]
	s_waitcnt lgkmcnt(2)
	v_mfma_f32_32x32x16_bf16 v[0:15], v[92:95], v[64:67], v[0:15]
	s_mov_b64 s[34:35], 0x80
	s_add_i32 s37, s37, 1
	v_lshl_add_u64 v[186:187], v[186:187], 0, s[34:35]
	v_lshl_add_u64 v[188:189], v[188:189], 0, s[34:35]
	s_mov_b64 s[34:35], 0x6000
	v_lshl_add_u64 v[190:191], v[190:191], 0, s[34:35]
	v_lshl_add_u64 v[192:193], v[192:193], 0, s[34:35]
	s_cmpk_eq_i32 s37, 0x84
	v_lshl_add_u64 v[194:195], v[194:195], 0, s[34:35]
	s_waitcnt lgkmcnt(0)
	s_barrier
	s_cbranch_scc1 .LBB0_129
